# zinit: redundant second zeroing of the compressed-branch accumulators dropped; zero / broadcast accumulator initialisations as packed pair moves
# baseline (speedup 1.0000x reference)
.LBB0_1007:
	s_mov_b32 s90, s20
	s_lshl_b32 s0, s23, 13
	s_lshl_b32 s1, s20, 4
	s_and_b32 s40, s22, 3
	s_bfe_u32 s29, s22, 0x10002
	s_bfe_u32 s98, s22, 0x1000b
	s_xor_b32 s29, s29, s98
	s_lshl_b32 s74, s75, 4
	s_and_b32 s0, s0, 0x6000
	s_ashr_i32 s20, s1, 31
	s_add_u32 s0, s1, s0
	s_addc_u32 s1, s20, 0
	v_or_b32_e32 v0, s0, v130
	s_lshl_b32 s0, s23, 1
	v_mov_b32_e32 v1, s1
	s_and_b32 s0, s0, 8
	s_lshr_b32 s98, s23, 8
	s_and_b32 s98, s98, 8
	s_xor_b32 s0, s0, s98
	v_add_u32_e32 v4, s0, v131
	v_lshlrev_b64 v[0:1], 12, v[0:1]
	v_lshl_add_u64 v[0:1], s[36:37], 0, v[0:1]
	v_lshlrev_b32_e32 v2, 7, v4
	v_mov_b32_e32 v3, v123
	v_lshl_add_u64 v[2:3], v[0:1], 0, v[2:3]
	v_mov_b32_e32 v133, v123
	v_lshl_add_u64 v[2:3], v[2:3], 0, v[132:133]
	global_load_dwordx4 v[48:51], v[2:3], off
	global_load_dwordx4 v[52:55], v[2:3], off offset:64
	v_mul_u32_u24_e32 v2, 3, v4
	v_lshlrev_b32_e32 v2, 1, v2
	v_mov_b32_e32 v3, v123
	v_lshl_add_u64 v[0:1], v[0:1], 0, v[2:3]
	global_load_dword v133, v[0:1], off offset:3584
	global_load_ushort v185, v[0:1], off offset:3588
	v_lshl_add_u32 v184, s29, 3, v131
	v_add_u32_e32 v0, 1, v184
	v_cvt_f32_ubyte0_e32 v0, v0
	v_mul_f32_e32 v1, -0.5, v0
	v_cmp_gt_f32_e32 vcc, s64, v1
	s_lshl_b32 s0, s40, 1
	s_or_b32 s47, s0, s29
	v_cndmask_b32_e32 v1, 0, v177, vcc
	v_fmac_f32_e32 v1, -0.5, v0
	v_exp_f32_e32 v0, v1
	s_add_i32 s0, s75, -1
	s_ashr_i32 s0, s0, 6
	s_add_i32 s0, s0, 1
	v_cndmask_b32_e32 v1, 0, v178, vcc
	s_cmp_gt_i32 s75, 0
	v_ldexp_f32 v0, v0, v1
	s_cselect_b32 s20, s0, 0
	v_pk_mov_b32 v[74:75], 0, 0
	v_mul_f32_e32 v146, 0x3fb8aa3b, v0
	v_or_b32_e32 v144, s74, v130
	s_cmp_lt_i32 s20, 1
	v_add_u32_e32 v187, 0xa000, v152
	v_add_u32_e32 v186, 0xc800, v152
	v_pk_mov_b32 v[72:73], 0, 0
	v_pk_mov_b32 v[78:79], 0, 0
	v_pk_mov_b32 v[76:77], 0, 0
	v_pk_mov_b32 v[70:71], 0, 0
	v_pk_mov_b32 v[68:69], 0, 0
	v_pk_mov_b32 v[66:67], 0, 0
	v_pk_mov_b32 v[64:65], 0, 0
	v_pk_mov_b32 v[80:81], 0, 0
	s_cbranch_scc1 .LBB0_1027
	s_lshl_b32 s21, s47, 16
	s_add_u32 s0, s3, s21
	s_addc_u32 s1, s52, 0
	s_add_u32 s22, s53, s21
	s_addc_u32 s23, s54, 0
	s_add_i32 s21, s20, -1
	s_cmp_eq_u32 s20, 1
	s_cselect_b64 s[24:25], -1, 0
	s_and_b64 vcc, s[24:25], exec
	s_cselect_b32 s26, 0, 64
	s_lshl_b32 s24, s26, 7
	v_mov_b32_e32 v135, v123
	s_add_u32 s24, s0, s24
	v_lshl_add_u64 v[0:1], s[0:1], 0, v[134:135]
	v_mov_b32_e32 v137, v123
	s_addc_u32 s25, s1, 0
	s_lshl_b32 s26, s26, 1
	v_lshl_add_u64 v[44:45], v[0:1], 0, v[122:123]
	v_lshl_add_u64 v[0:1], s[22:23], 0, v[136:137]
	s_add_u32 s26, s22, s26
	v_lshl_add_u64 v[46:47], v[0:1], 0, v[122:123]
	s_addc_u32 s27, s23, 0
	v_lshl_add_u64 v[0:1], s[24:25], 0, v[134:135]
	v_mov_b32_e32 v8, v240
	v_mov_b32_e32 v9, v241
	v_mov_b32_e32 v10, v242
	v_mov_b32_e32 v11, v243
	v_mov_b32_e32 v12, v244
	v_mov_b32_e32 v13, v245
	v_mov_b32_e32 v14, v246
	v_mov_b32_e32 v15, v247
	v_lshl_add_u64 v[0:1], v[0:1], 0, v[122:123]
	v_lshl_add_u64 v[2:3], s[26:27], 0, v[136:137]
	v_lshl_add_u64 v[2:3], v[2:3], 0, v[122:123]
	v_mov_b32_e32 v16, v248
	v_mov_b32_e32 v17, v249
	v_mov_b32_e32 v18, v250
	v_mov_b32_e32 v19, v251
	v_mov_b32_e32 v20, v252
	v_mov_b32_e32 v21, v253
	v_mov_b32_e32 v22, v254
	v_mov_b32_e32 v23, v255
	s_min_u32 s26, s21, 2
	s_lshl_b32 s24, s26, 13
	s_add_u32 s24, s0, s24
	s_addc_u32 s25, s1, 0
	s_lshl_b32 s26, s26, 7
	s_add_u32 s26, s22, s26
	v_lshl_add_u64 v[0:1], s[24:25], 0, v[134:135]
	s_addc_u32 s27, s23, 0
	s_min_u32 s24, s21, 3
	s_lshl_b32 s25, s24, 13
	s_add_u32 s0, s0, s25
	v_lshl_add_u64 v[2:3], s[26:27], 0, v[136:137]
	s_addc_u32 s1, s1, 0
	s_lshl_b32 s24, s24, 7
	v_lshl_add_u64 v[0:1], v[0:1], 0, v[122:123]
	v_lshl_add_u64 v[2:3], v[2:3], 0, v[122:123]
	s_add_u32 s22, s22, s24
	global_load_dwordx4 v[4:7], v[0:1], off
	s_nop 0
	global_load_dwordx4 v[0:3], v[2:3], off
	v_lshl_add_u64 v[24:25], s[0:1], 0, v[134:135]
	s_addc_u32 s23, s23, 0
	v_lshl_add_u64 v[24:25], v[24:25], 0, v[122:123]
	v_lshl_add_u64 v[26:27], s[22:23], 0, v[136:137]
	v_lshl_add_u64 v[26:27], v[26:27], 0, v[122:123]
	s_mov_b32 s0, 0
	ds_write_b128 v151, v[8:11]
	ds_write2_b64 v187, v[12:13], v[14:15] offset1:2
	ds_write_b128 v151, v[16:19] offset:10240
	ds_write2_b64 v186, v[20:21], v[22:23] offset1:2
	global_load_dwordx4 v[12:15], v[24:25], off
	global_load_dwordx4 v[8:11], v[26:27], off
	s_waitcnt lgkmcnt(0)
	s_barrier
	s_cbranch_vccnz .LBB0_1021
	v_mov_b32_e32 v80, 0
	s_add_i32 s22, s75, -2
	v_mul_f32_e32 v82, 0x41800000, v146
	v_mul_f32_e32 v83, 0x42000000, v146
	v_mul_f32_e32 v84, 0x42400000, v146
	v_mul_f32_e32 v85, 0, v146
	s_waitcnt lgkmcnt(7)
	v_mul_f32_e32 v86, 0x43800000, v146
	v_mul_f32_e32 v87, 0x44000000, v146
	v_mul_f32_e32 v88, 0x44400000, v146
	v_add_u32_e32 v89, s74, v169
	s_mov_b32 s24, 5
	s_movk_i32 s23, 0xc0
	v_mov_b32_e32 v81, 0
	v_mov_b32_e32 v64, 0
	v_mov_b32_e32 v65, v80
	v_mov_b32_e32 v66, v80
	v_mov_b32_e32 v67, v80
	v_mov_b32_e32 v68, 0
	v_mov_b32_e32 v69, v80
	v_mov_b32_e32 v70, v80
	v_mov_b32_e32 v71, v80
	v_mov_b32_e32 v76, 0
	v_mov_b32_e32 v77, v80
	v_mov_b32_e32 v78, v80
	v_mov_b32_e32 v79, v80
	v_mov_b32_e32 v72, 0
	v_mov_b32_e32 v73, v80
	v_mov_b32_e32 v74, v80
	v_mov_b32_e32 v75, v80

.LBB0_1038:
	s_or_b64 exec, exec, s[0:1]
	s_bcnt1_i32_b32 s0, s21
	s_bcnt1_i32_b32 s1, s22
	s_bcnt1_i32_b32 s21, s23
	s_lshl_b32 s22, s40, 25
	s_add_u32 s22, s36, s22
	s_addc_u32 s23, s37, 0
	s_bcnt1_i32_b32 s20, s20
	s_add_i32 s0, s0, s20
	s_add_i32 s79, s0, s1
	s_add_i32 s79, s79, s21
	s_lshl_b32 s0, s29, 7
	s_add_u32 s24, s22, s0
	v_sub_co_u32_e64 v32, s[0:1], s79, 1
	s_waitcnt lgkmcnt(0)
	s_barrier
	s_addc_u32 s25, s23, 0
	s_lshl_b32 s0, s47, 20
	s_add_u32 s20, s55, s0
	s_addc_u32 s21, s56, 0
	v_add_u32_e32 v8, -2, v32
	v_max_i32_e32 v8, 0, v8
	v_add_u32_e32 v9, -3, v32
	v_max_i32_e32 v9, 0, v9
	v_lshl_add_u32 v8, v8, 2, s72
	v_lshl_add_u32 v9, v9, 2, s72
	ds_read_b32 v8, v8
	ds_read_b32 v9, v9
	s_ashr_i32 s32, s75, 2
	s_add_i32 s97, s32, -1
	s_max_i32 s97, s97, 0
	s_cmp_lt_u32 s79, 2
	s_cselect_b64 vcc, -1, 0
	v_mov_b32_e32 v139, v123
	v_mov_b32_e32 v141, v123
	v_readfirstlane_b32 s80, v32
	v_add_f32_e32 v137, v146, v146
	v_mul_f32_e32 v188, 0x40400000, v146
	v_mul_f32_e32 v189, 0x41800000, v146
	v_mul_f32_e32 v190, 0x42000000, v146
	v_mul_f32_e32 v191, 0x42400000, v146
	v_mul_f32_e32 v192, 0, v146
	s_waitcnt vmcnt(0)
	ds_write_b128 v151, v[240:243]
	ds_write2_b64 v187, v[244:245], v[246:247] offset1:2
	ds_write_b128 v151, v[248:251] offset:10240
	ds_write2_b64 v186, v[252:253], v[254:255] offset1:2
	s_lshl_b32 s98, s47, 20
	s_add_u32 s98, s57, s98
	s_addc_u32 s99, s60, 0
	s_add_i32 s29, s74, 0xfffffe01
	s_andn2_b32 s29, s29, 63
	s_cmp_gt_i32 s75, 31
	s_cselect_b32 s29, s29, 0
	s_sub_i32 s30, s74, s29
	s_ashr_i32 s30, s30, 6
	v_mov_b32_e32 v4, v138
	v_mov_b32_e32 v5, 0
	v_mov_b32_e32 v6, v140
	v_mov_b32_e32 v7, 0
	s_min_i32 s22, s30, 0
	s_lshl_b32 s22, s22, 6
	s_add_i32 s22, s22, s29
	s_ashr_i32 s23, s22, 31
	s_lshl_b64 s[100:101], s[22:23], 12
	s_add_u32 s100, s24, s100
	s_addc_u32 s101, s25, s101
	s_lshl_b64 s[22:23], s[22:23], 1
	s_add_u32 s22, s98, s22
	s_addc_u32 s23, s99, s23
	v_lshl_add_u64 v[0:1], s[100:101], 0, v[4:5]
	v_lshl_add_u64 v[2:3], s[22:23], 0, v[6:7]
	v_lshl_add_u64 v[0:1], v[0:1], 0, v[122:123]
	v_lshl_add_u64 v[2:3], v[2:3], 0, v[122:123]
	global_load_dwordx4 v[240:243], v[0:1], off offset:3072
	global_load_dwordx4 v[244:247], v[2:3], off
	s_min_i32 s22, s30, 1
	s_lshl_b32 s22, s22, 6
	s_add_i32 s22, s22, s29
	s_ashr_i32 s23, s22, 31
	s_lshl_b64 s[100:101], s[22:23], 12
	s_add_u32 s100, s24, s100
	s_addc_u32 s101, s25, s101
	s_lshl_b64 s[22:23], s[22:23], 1
	s_add_u32 s22, s98, s22
	s_addc_u32 s23, s99, s23
	v_lshl_add_u64 v[0:1], s[100:101], 0, v[4:5]
	v_lshl_add_u64 v[2:3], s[22:23], 0, v[6:7]
	v_lshl_add_u64 v[0:1], v[0:1], 0, v[122:123]
	v_lshl_add_u64 v[2:3], v[2:3], 0, v[122:123]
	global_load_dwordx4 v[248:251], v[0:1], off offset:3072
	global_load_dwordx4 v[252:255], v[2:3], off
	s_waitcnt lgkmcnt(4)
	v_readfirstlane_b32 s89, v8
	v_readfirstlane_b32 s91, v9
	s_lshl_b32 s0, s89, 6
	s_ashr_i32 s1, s0, 31
	s_lshl_b64 s[22:23], s[0:1], 12
	s_add_u32 s22, s24, s22
	s_addc_u32 s23, s25, s23
	s_lshl_b64 s[0:1], s[0:1], 1
	s_add_u32 s0, s20, s0
	s_addc_u32 s1, s21, s1
	v_lshl_add_u64 v[0:1], s[22:23], 0, v[138:139]
	v_lshl_add_u64 v[2:3], s[0:1], 0, v[140:141]
	v_lshl_add_u64 v[0:1], v[0:1], 0, v[122:123]
	v_lshl_add_u64 v[2:3], v[2:3], 0, v[122:123]
	global_load_dwordx4 v[20:23], v[0:1], off offset:2560
	global_load_dwordx4 v[16:19], v[2:3], off
	s_lshl_b32 s0, s91, 6
	s_ashr_i32 s1, s0, 31
	s_lshl_b64 s[22:23], s[0:1], 12
	s_add_u32 s22, s24, s22
	s_addc_u32 s23, s25, s23
	s_lshl_b64 s[0:1], s[0:1], 1
	s_add_u32 s0, s20, s0
	s_addc_u32 s1, s21, s1
	v_lshl_add_u64 v[4:5], s[22:23], 0, v[138:139]
	v_lshl_add_u64 v[6:7], s[0:1], 0, v[140:141]
	v_lshl_add_u64 v[4:5], v[4:5], 0, v[122:123]
	v_lshl_add_u64 v[6:7], v[6:7], 0, v[122:123]
	global_load_dwordx4 v[28:31], v[4:5], off offset:2560
	global_load_dwordx4 v[24:27], v[6:7], off
	s_waitcnt lgkmcnt(0)
	s_barrier
	v_lshl_add_u64 v[0:1], s[24:25], 0, v[138:139]
	v_lshl_add_u64 v[120:121], v[0:1], 0, v[122:123]
	s_and_b64 vcc, exec, vcc
	s_cbranch_vccnz .LBB0_1050
	v_lshl_add_u64 v[0:1], s[20:21], 0, v[140:141]
	v_mov_b32_e32 v36, 0
	v_lshl_add_u64 v[148:149], v[0:1], 0, v[122:123]
	v_sub_u32_e32 v139, v144, v124
	v_mov_b32_e32 v32, v123
	v_mov_b32_e32 v33, v123
	v_mov_b32_e32 v34, v123
	v_mov_b32_e32 v35, v123
	s_mov_b32 s83, 5
	s_movk_i32 s81, 0x80
	s_mov_b32 s82, s72
	v_mov_b32_e32 v37, v36
	v_pk_mov_b32 v[38:39], v[36:37], v[36:37] op_sel:[0,0] op_sel_hi:[0,0]
	v_pk_mov_b32 v[40:41], v[36:37], v[36:37] op_sel:[0,0] op_sel_hi:[0,0]
	v_pk_mov_b32 v[42:43], v[36:37], v[36:37] op_sel:[0,0] op_sel_hi:[0,0]
	v_pk_mov_b32 v[44:45], v[36:37], v[36:37] op_sel:[0,0] op_sel_hi:[0,0]
	v_pk_mov_b32 v[46:47], v[36:37], v[36:37] op_sel:[0,0] op_sel_hi:[0,0]
	v_pk_mov_b32 v[84:85], v[36:37], v[36:37] op_sel:[0,0] op_sel_hi:[0,0]
	v_pk_mov_b32 v[86:87], v[36:37], v[36:37] op_sel:[0,0] op_sel_hi:[0,0]

.LBB0_1059:
	s_lshl_b32 s0, s80, 1
	s_add_u32 s0, s57, s0
	s_addc_u32 s1, s60, 0
	s_add_i32 s20, s74, 0xfffffe01
	s_andn2_b32 s20, s20, 63
	s_cmp_gt_i32 s75, 31
	s_cselect_b32 s20, s20, 0
	s_sub_i32 s21, s74, s20
	s_ashr_i32 s21, s21, 6
	s_min_i32 s22, s21, 0
	s_lshl_b32 s22, s22, 6
	s_add_i32 s22, s22, s20
	s_ashr_i32 s23, s22, 31
	s_lshl_b64 s[26:27], s[22:23], 12
	s_add_u32 s26, s24, s26
	s_addc_u32 s27, s25, s27
	s_lshl_b64 s[22:23], s[22:23], 1
	s_add_u32 s22, s0, s22
	s_addc_u32 s23, s1, s23
	v_mov_b32_e32 v141, v123
	s_waitcnt vmcnt(2)
	v_lshl_add_u64 v[18:19], s[22:23], 0, v[140:141]
	s_min_i32 s22, s21, 1
	s_lshl_b32 s22, s22, 6
	s_add_i32 s22, s22, s20
	v_mov_b32_e32 v139, v123
	s_ashr_i32 s23, s22, 31
	v_lshl_add_u64 v[16:17], s[26:27], 0, v[138:139]
	s_lshl_b64 s[26:27], s[22:23], 12
	s_add_u32 s26, s24, s26
	s_addc_u32 s27, s25, s27
	s_lshl_b64 s[22:23], s[22:23], 1
	s_add_u32 s22, s0, s22
	s_addc_u32 s23, s1, s23
	v_lshl_add_u64 v[16:17], v[16:17], 0, v[122:123]
	v_lshl_add_u64 v[20:21], v[18:19], 0, v[122:123]
	s_waitcnt vmcnt(0)
	v_lshl_add_u64 v[24:25], s[26:27], 0, v[138:139]
	v_lshl_add_u64 v[26:27], s[22:23], 0, v[140:141]
	v_mov_b32_e32 v16, v240
	v_mov_b32_e32 v17, v241
	v_mov_b32_e32 v18, v242
	v_mov_b32_e32 v19, v243
	s_nop 0
	v_mov_b32_e32 v20, v244
	v_mov_b32_e32 v21, v245
	v_mov_b32_e32 v22, v246
	v_mov_b32_e32 v23, v247
	v_lshl_add_u64 v[24:25], v[24:25], 0, v[122:123]
	v_lshl_add_u64 v[28:29], v[26:27], 0, v[122:123]
	v_mov_b32_e32 v24, v248
	v_mov_b32_e32 v25, v249
	v_mov_b32_e32 v26, v250
	v_mov_b32_e32 v27, v251
	s_nop 0
	v_mov_b32_e32 v28, v252
	v_mov_b32_e32 v29, v253
	v_mov_b32_e32 v30, v254
	v_mov_b32_e32 v31, v255
	s_min_i32 s22, s21, 2
	s_lshl_b32 s22, s22, 6
	s_add_i32 s22, s22, s20
	s_ashr_i32 s23, s22, 31
	s_lshl_b64 s[26:27], s[22:23], 12
	s_add_u32 s26, s24, s26
	s_addc_u32 s27, s25, s27
	s_lshl_b64 s[22:23], s[22:23], 1
	s_add_u32 s22, s0, s22
	s_waitcnt lgkmcnt(3)
	v_lshl_add_u64 v[32:33], s[26:27], 0, v[138:139]
	s_addc_u32 s23, s1, s23
	s_min_i32 s26, s21, 3
	v_lshl_add_u64 v[34:35], s[22:23], 0, v[140:141]
	s_lshl_b32 s22, s26, 6
	s_add_i32 s22, s22, s20
	s_ashr_i32 s23, s22, 31
	s_lshl_b64 s[26:27], s[22:23], 12
	s_add_u32 s24, s24, s26
	s_addc_u32 s25, s25, s27
	s_lshl_b64 s[22:23], s[22:23], 1
	s_add_u32 s22, s0, s22
	v_lshl_add_u64 v[32:33], v[32:33], 0, v[122:123]
	v_lshl_add_u64 v[34:35], v[34:35], 0, v[122:123]
	s_addc_u32 s23, s1, s23
	s_waitcnt lgkmcnt(2)
	global_load_dwordx4 v[36:39], v[32:33], off offset:3072
	s_nop 0
	global_load_dwordx4 v[32:35], v[34:35], off
	s_waitcnt lgkmcnt(1)
	v_lshl_add_u64 v[40:41], s[24:25], 0, v[138:139]
	v_lshl_add_u64 v[42:43], s[22:23], 0, v[140:141]
	v_lshl_add_u64 v[40:41], v[40:41], 0, v[122:123]
	v_lshl_add_u64 v[42:43], v[42:43], 0, v[122:123]
	s_mov_b32 s23, 0
	s_cmp_lt_i32 s21, 1
	s_mov_b32 s24, 0
	s_waitcnt vmcnt(5)
	ds_write_b128 v151, v[16:19]
	s_waitcnt vmcnt(4)
	ds_write2_b64 v187, v[20:21], v[22:23] offset1:2
	s_waitcnt vmcnt(3)
	ds_write_b128 v151, v[24:27] offset:10240
	s_waitcnt vmcnt(2)
	ds_write2_b64 v186, v[28:29], v[30:31] offset1:2
	s_waitcnt lgkmcnt(4)
	global_load_dwordx4 v[44:47], v[40:41], off offset:3072
	s_nop 0
	global_load_dwordx4 v[40:43], v[42:43], off
	s_cselect_b32 s91, 1, 0
	s_add_i32 s98, s90, -1
	s_ashr_i32 s98, s98, 6
	s_cmp_gt_i32 s98, 0
	s_cselect_b32 s99, 0x2000, 0
	s_cselect_b32 s98, 0x80, 0
	s_and_b32 s29, s73, 3
	s_lshl_b32 s29, s29, 1
	s_bfe_u32 s30, s73, 0x10002
	s_or_b32 s29, s29, s30
	s_bfe_u32 s30, s73, 0x1000b
	s_xor_b32 s29, s29, s30
	s_lshl_b32 s29, s29, 16
	s_add_u32 s100, s3, s29
	s_addc_u32 s101, s52, 0
	s_add_u32 s30, s53, s29
	s_addc_u32 s31, s54, 0
	v_mov_b32_e32 v194, v134
	v_mov_b32_e32 v195, 0
	v_mov_b32_e32 v196, v136
	v_mov_b32_e32 v197, 0
	v_lshl_add_u64 v[198:199], s[100:101], 0, v[194:195]
	v_lshl_add_u64 v[200:201], s[30:31], 0, v[196:197]
	v_lshl_add_u64 v[198:199], v[198:199], 0, v[122:123]
	v_lshl_add_u64 v[200:201], v[200:201], 0, v[122:123]
	global_load_dwordx4 v[240:243], v[198:199], off
	global_load_dwordx4 v[244:247], v[200:201], off
	s_add_u32 s100, s100, s99
	s_addc_u32 s101, s101, 0
	s_add_u32 s30, s30, s98
	s_addc_u32 s31, s31, 0
	v_lshl_add_u64 v[198:199], s[100:101], 0, v[194:195]
	v_lshl_add_u64 v[200:201], s[30:31], 0, v[196:197]
	v_lshl_add_u64 v[198:199], v[198:199], 0, v[122:123]
	v_lshl_add_u64 v[200:201], v[200:201], 0, v[122:123]
	global_load_dwordx4 v[248:251], v[198:199], off
	global_load_dwordx4 v[252:255], v[200:201], off
	s_cmp_lg_u32 s91, 0
	s_waitcnt lgkmcnt(0)
	s_barrier
	s_cbranch_scc1 .LBB0_1068
	v_lshl_add_u64 v[16:17], s[0:1], 0, v[140:141]
	v_lshl_add_u64 v[106:107], v[16:17], 0, v[122:123]
	v_add_u32_e32 v16, s74, v171
	v_mov_b32_e32 v86, 0
	s_add_i32 s22, s74, 0xfffffe10
	v_subrev_u32_e32 v81, s20, v16
	v_mov_b32_e32 v87, v86
	v_mov_b32_e32 v88, v86
	v_mov_b32_e32 v89, v86
	s_mov_b32 s23, 5
	v_pk_mov_b32 v[90:91], v[86:87], v[86:87] op_sel:[0,0] op_sel_hi:[0,0]
	v_pk_mov_b32 v[92:93], v[86:87], v[86:87] op_sel:[0,0] op_sel_hi:[0,0]
	v_pk_mov_b32 v[94:95], v[86:87], v[86:87] op_sel:[0,0] op_sel_hi:[0,0]
	v_pk_mov_b32 v[96:97], v[86:87], v[86:87] op_sel:[0,0] op_sel_hi:[0,0]
	v_pk_mov_b32 v[98:99], v[86:87], v[86:87] op_sel:[0,0] op_sel_hi:[0,0]
	v_pk_mov_b32 v[100:101], v[86:87], v[86:87] op_sel:[0,0] op_sel_hi:[0,0]
	v_pk_mov_b32 v[102:103], v[86:87], v[86:87] op_sel:[0,0] op_sel_hi:[0,0]
	v_pk_mov_b32 v[104:105], v[86:87], v[86:87] op_sel:[0,0] op_sel_hi:[0,0]
